# v64 + diff loops: rescale / near-diagonal bias blocks moved out of line, their tests reduced to one unsigned range compare, loop counter test by carry
# speedup vs baseline: 1.0584x; 1.0044x over previous
; DI float bf2f(unsigned short h) { return __uint_as_float((unsigned)h << 16); }
; template <int DQK, int MODE, int LDQ, int LDK, int LDV> ...
;     ...
;     float l_reg = 0.f; f32x16 o[4];
; #pragma unroll
;     for (int d = 0; d < 4; ++d)
; #pragma unroll
;         for (int r = 0; r < 16; ++r) o[d][r] = 0.f;
;     int kgo[NKP], vgo[2];
; #pragma unroll
;     for (int i = 0; i < NKP; ++i) { const int L = (wid + 8 * i) * 64 + lane, row = L / CPR, slot = L % CPR, cc = (slot & ~7) | ((slot & 7) ^ ((row >> 1) & 7)); kgo[i] = row * LDK + cc * 8; }
; #pragma unroll
;     for (int i = 0; i < 2; ++i) { const int L = (2 * wid + i) * 64 + lane, st = L >> 5, w5 = L & 31, kk = (st >> 2) * 8 + (w5 >> 2), c = (st & 3) * 32 + (w5 & 3) * 8;
;         const int k = (kk & ~0xC) | ((kk & 4) << 1) | ((kk & 8) >> 1); vgo[i] = k * LDV + c; }
;     ...
;     ATT_DMA_K(0); ATT_DMA_K(1); ATT_DMA_V(0, 0); ATT_DMA_K(2); ATT_DMA_V(1, 1);
;     bf16x8 qr[ND0];
;     { const bf16_t* Qw = Qb + (size_t)(wid * 32 + r32) * LDQ + hi * 8;
; #pragma unroll
;       for (int d0 = 0; d0 < ND0; ++d0) qr[d0] = *(const bf16x8*)(Qw + d0 * 16);
;       if constexpr (MODE == 0) {
;           float ss = 0.f;
; #pragma unroll
;           for (int d0 = 0; d0 < ND0; ++d0)
; #pragma unroll
;               for (int j = 0; j < 8; ++j) { const float f = bf2f((unsigned short)qr[d0][j]); ss += f * f; }
;           ss = swap_sum(ss);
;           const float rstd = rsqrtf(ss * (1.f / DQK) + EPS) * C;
; #pragma unroll
;           for (int d0 = 0; d0 < ND0; ++d0) { const float* g = gq + d0 * 16 + hi * 8;
;               { float f[8]; _Pragma("unroll") for (int j = 0; j < 8; ++j) f[j] = bf2f((unsigned short)qr[d0][j]) * rstd * g[j];
;                 u32x4 w = {cvtpk(f[0], f[1]), cvtpk(f[2], f[3]), cvtpk(f[4], f[5]), cvtpk(f[6], f[7])}; qr[d0] = __builtin_bit_cast(bf16x8, w); asm volatile("" ::: "memory"); } }
;       } }
;     const int qlo = q0 + wid * 32, qpos = qlo + r32;
;     const int tL = MODE == 0 ? 0 : (qlo >= 191 ? (qlo - 127) >> 6 : 0), tR = MODE == 0 ? NT : min(NT, (qlo + 222) >> 6);
;     float fL = 1.f, fR = 1.f; if constexpr (MODE != 0) { fL = __builtin_amdgcn_exp2f(bt[0]); fR = __builtin_amdgcn_exp2f(-bt[448]); }
;     ...
;     const int vbase = (int)(unsigned)(size_t)lds + V_OFF + v_rd_base(lane);
.LBB0_1919:
	s_lshl_b32 s87, s86, 7
	s_and_b32 s54, s0, 0xffffffc0
	s_min_i32 s97, s58, 64
	s_and_b32 s92, s73, 0xf00
	s_cmp_gt_i32 s55, 0
	s_cselect_b64 s[4:5], -1, 0
	s_add_i32 s93, 0, 0x18000
	s_add_i32 s1, s92, s94
	s_add_u32 s90, s2, s84
	v_add_lshl_u32 v2, s1, v2, 2
	s_addc_u32 s91, s3, 0
	v_readlane_b32 s1, v255, 6
	s_add_u32 s2, s1, s90
	s_addc_u32 s3, s76, s91
	s_add_i32 s7, s7, s6
	v_lshl_add_u64 v[100:101], v[0:1], 1, s[2:3]
	v_subrev_u32_e32 v100, s34, v100
	v_add3_u32 v0, s7, v6, v4
	v_lshl_or_b32 v0, v0, 11, v3
	v_and_b32_e32 v7, 63, v7
	v_add_u32_e32 v0, v0, v5
	s_add_u32 s2, s77, s90
	v_exp_f32_e32 v112, v9
	v_lshlrev_b32_e32 v8, 3, v7
	v_lshlrev_b32_e32 v9, 4, v7
	v_lshlrev_b32_e32 v7, 1, v7
	v_ashrrev_i32_e32 v1, 31, v0
	s_addc_u32 s3, s78, s91
	v_exp_f32_e64 v113, -v10
	v_and_b32_e32 v7, 32, v7
	v_lshl_add_u64 v[102:103], v[0:1], 1, s[2:3]
	v_subrev_u32_e32 v102, s34, v102
	v_add_u32_e32 v0, 64, v0
	v_and_b32_e32 v9, 0xc0, v9
	v_and_or_b32 v7, v8, s66, v7
	v_sub_u32_e32 v2, v130, v2
	v_ashrrev_i32_e32 v1, 31, v0
	v_mov_b32_e32 v14, v131
	v_mov_b32_e32 v15, v131
	v_add3_u32 v106, v9, s93, v7
	v_add_u32_e32 v119, 0, v2
	v_lshl_add_u64 v[104:105], v[0:1], 1, s[2:3]
	v_subrev_u32_e32 v104, s34, v104
	v_mov_b32_e32 v0, v131
	v_mov_b32_e32 v1, v131
	v_mov_b32_e32 v2, v131
	v_mov_b32_e32 v3, v131
	v_mov_b32_e32 v4, v131
	v_mov_b32_e32 v5, v131
	v_mov_b32_e32 v6, v131
	v_mov_b32_e32 v7, v131
	v_mov_b32_e32 v8, v131
	v_mov_b32_e32 v9, v131
	v_mov_b32_e32 v10, v131
	v_mov_b32_e32 v11, v131
	v_mov_b32_e32 v12, v131
	v_mov_b32_e32 v13, v131
	v_mov_b64_e32 v[62:63], v[14:15]
	v_mov_b64_e32 v[46:47], v[14:15]
	v_mov_b64_e32 v[30:31], v[14:15]
	s_mov_b32 s0, 1
	s_mov_b32 s23, 0
	s_mov_b32 s96, 2
	s_sub_i32 s62, 0, s55
	s_sub_i32 s6, 0, s97
	v_mov_b32_e32 v120, 0
	s_movk_i32 s7, 0xc300
	s_movk_i32 s22, 0x6000
	s_add_i32 s98, s55, 1
	s_add_i32 s99, s97, 1
	s_sub_i32 s101, s97, s55
	s_max_i32 s100, s101, 0
	v_mov_b32_e32 v196, v107
	v_mov_b32_e32 v197, v108
	v_mov_b32_e32 v198, v109
	v_mov_b32_e32 v199, v110
	v_mov_b64_e32 v[60:61], v[12:13]
	v_mov_b64_e32 v[58:59], v[10:11]
	v_mov_b64_e32 v[56:57], v[8:9]
	v_mov_b64_e32 v[54:55], v[6:7]
	v_mov_b64_e32 v[52:53], v[4:5]
	v_mov_b64_e32 v[50:51], v[2:3]
	v_mov_b64_e32 v[48:49], v[0:1]
	v_mov_b64_e32 v[44:45], v[12:13]
	v_mov_b64_e32 v[42:43], v[10:11]
	v_mov_b64_e32 v[40:41], v[8:9]
	v_mov_b64_e32 v[38:39], v[6:7]
	v_mov_b64_e32 v[36:37], v[4:5]
	v_mov_b64_e32 v[34:35], v[2:3]
	v_mov_b64_e32 v[32:33], v[0:1]
	v_mov_b64_e32 v[28:29], v[12:13]
	v_mov_b64_e32 v[26:27], v[10:11]
	v_mov_b64_e32 v[24:25], v[8:9]
	v_mov_b64_e32 v[22:23], v[6:7]
	v_mov_b64_e32 v[20:21], v[4:5]
	v_mov_b64_e32 v[18:19], v[2:3]
	v_mov_b64_e32 v[16:17], v[0:1]
	s_mov_b32 s64, 1
	s_cmp_lt_u32 s33, 0x100
	s_cbranch_scc1 .Lstg_d0_pre_9
	s_waitcnt vmcnt(3)
	s_barrier

; #define LAS __attribute__((address_space(3)))
; DI void expsum(f32x16& p, float& l_reg, bf16x8& pa0, bf16x8& pa1) {
; #pragma unroll
;     for (int r = 0; r < 16; ++r) p[r] = __builtin_amdgcn_exp2f(p[r]);
;     float ps = 0.f;
; #pragma unroll
;     for (int r = 0; r < 16; ++r) ps += p[r];
;     l_reg += ps; asm volatile("" : "+v"(l_reg));
;     ...
;     ATT_PK4(p, 0, pa0); ATT_PK4(p, 8, pa1);
;     ...
; }
; DI int v_rd_base(int lane) { return ((lane & 3) << 3) | (((lane >> 2) & 3) << 6) | (((lane >> 4) & 1) << 5) | (((lane >> 5) & 1) << 8); }
; template <int OFF> DI s16x4 tr_read(int vb) { s16x4 r; asm volatile("ds_read_b64_tr_b16 %0, %1 offset:%2" : "=&v"(r) : "v"(vb), "i"(OFF) : "memory"); return r; }
; template <int H> DI void v_reads(s16x4* vf, int vb) {
;     vf[0] = tr_read<v_rd_off(0, 2 * H, 0)>(vb); vf[1] = tr_read<v_rd_off(0, 2 * H, 1)>(vb); vf[2] = tr_read<v_rd_off(0, 2 * H + 1, 0)>(vb); vf[3] = tr_read<v_rd_off(0, 2 * H + 1, 1)>(vb);
;     vf[4] = tr_read<v_rd_off(1, 2 * H, 0)>(vb); vf[5] = tr_read<v_rd_off(1, 2 * H, 1)>(vb); vf[6] = tr_read<v_rd_off(1, 2 * H + 1, 0)>(vb); vf[7] = tr_read<v_rd_off(1, 2 * H + 1, 1)>(vb);
;     vf[8] = tr_read<v_rd_off(2, 2 * H, 0)>(vb); vf[9] = tr_read<v_rd_off(2, 2 * H, 1)>(vb); vf[10] = tr_read<v_rd_off(2, 2 * H + 1, 0)>(vb); vf[11] = tr_read<v_rd_off(2, 2 * H + 1, 1)>(vb);
;     vf[12] = tr_read<v_rd_off(3, 2 * H, 0)>(vb); vf[13] = tr_read<v_rd_off(3, 2 * H, 1)>(vb); vf[14] = tr_read<v_rd_off(3, 2 * H + 1, 0)>(vb); vf[15] = tr_read<v_rd_off(3, 2 * H + 1, 1)>(vb);
; }
; DI void pv_mma(f32x16* o, const s16x4* vf, bf16x8 pa0, bf16x8 pa1) {
;     ...
; #pragma unroll
;     for (int d0 = 0; d0 < 4; ++d0) {
;         o[d0] = __builtin_amdgcn_mfma_f32_32x32x16_bf16(pa0, ATT_PK(vf[4 * d0], vf[4 * d0 + 1]), o[d0], 0, 0, 0);
;         o[d0] = __builtin_amdgcn_mfma_f32_32x32x16_bf16(pa1, ATT_PK(vf[4 * d0 + 2], vf[4 * d0 + 3]), o[d0], 0, 0, 0); }
;     ...
; }
; template <int DQK, int D0A, int D0B> DI void k_reads(bf16x8* kf, const LAS unsigned char* Ks, int half, int r32, int hi) {
; #pragma unroll
;     for (int d0 = D0A; d0 < D0B; ++d0) kf[d0 - D0A] = *(const LAS bf16x8*)(Ks + half * (32 * DQK * 2) + kswz<DQK>(r32, (d0 * 16 + hi * 8) * 2));
; }
; template <int D0A, int D0B> DI void qk_mma(f32x16& p, const bf16x8* kf, const bf16x8* qr) {
; #pragma unroll
;     for (int d0 = D0A; d0 < D0B; ++d0) {
.Lstg_d0_top_10:
	s_setprio 0
	s_add_i32 s1, s95, s1
	global_load_lds_dwordx4 v100, s[34:35]
	s_add_i32 s2, s1, 0x400
	s_mov_b32 m0, s1
	s_sub_i32 s74, s0, s98
	global_load_lds_dwordx4 v102, s[34:35]
	s_mov_b32 m0, s2
	s_cmp_le_u32 s74, s101
	global_load_lds_dwordx4 v104, s[34:35]
	s_mov_b32 s1, s23
	s_cbranch_scc1 .Ldt_d0_resc
.LBB0_1922:
	ds_read_b128 v[122:125], v196 offset:4096
	ds_read_b128 v[132:135], v197 offset:4096
	s_lshl_b32 s2, s1, 14
	ds_read_b128 v[136:139], v198 offset:4096
	ds_read_b128 v[140:143], v199 offset:4096
	v_add_u32_e32 v121, s2, v106
	ds_read_b64_tr_b16 v[144:145], v121 offset:0
	ds_read_b64_tr_b16 v[146:147], v121 offset:0x800
	ds_read_b64_tr_b16 v[148:149], v121 offset:0x1000
	ds_read_b64_tr_b16 v[150:151], v121 offset:0x1800
	ds_read_b64_tr_b16 v[152:153], v121 offset:0x200
	ds_read_b64_tr_b16 v[154:155], v121 offset:0xa00
	ds_read_b64_tr_b16 v[156:157], v121 offset:0x1200
	ds_read_b64_tr_b16 v[158:159], v121 offset:0x1a00
	ds_read_b64_tr_b16 v[162:163], v121 offset:0x400
	ds_read_b64_tr_b16 v[164:165], v121 offset:0xc00
	ds_read_b64_tr_b16 v[166:167], v121 offset:0x1400
	ds_read_b64_tr_b16 v[168:169], v121 offset:0x1c00
	ds_read_b64_tr_b16 v[170:171], v121 offset:0x600
	ds_read_b64_tr_b16 v[172:173], v121 offset:0xe00
	ds_read_b64_tr_b16 v[174:175], v121 offset:0x1600
	ds_read_b64_tr_b16 v[176:177], v121 offset:0x1e00
	s_setprio 2
	v_exp_f32_e32 v64, v64
	v_exp_f32_e32 v65, v65
	v_exp_f32_e32 v66, v66
	v_exp_f32_e32 v67, v67
	v_exp_f32_e32 v68, v68
	v_exp_f32_e32 v69, v69
	v_add_f32_e32 v126, v65, v64
	v_exp_f32_e32 v70, v70
	v_add_f32_e32 v126, v66, v126
	v_exp_f32_e32 v71, v71
	v_add_f32_e32 v126, v67, v126
	v_exp_f32_e32 v72, v72
	v_add_f32_e32 v126, v68, v126
	v_exp_f32_e32 v73, v73
	v_add_f32_e32 v126, v69, v126
	v_exp_f32_e32 v74, v74
	v_add_f32_e32 v126, v70, v126
	v_exp_f32_e32 v75, v75
	v_add_f32_e32 v126, v71, v126
	v_exp_f32_e32 v76, v76
	v_add_f32_e32 v126, v72, v126
	v_exp_f32_e32 v77, v77
	v_add_f32_e32 v126, v73, v126
	v_exp_f32_e32 v78, v78
	v_add_f32_e32 v126, v74, v126
	v_exp_f32_e32 v79, v79
	v_add_f32_e32 v126, v75, v126
	v_add_f32_e32 v126, v76, v126
	v_add_f32_e32 v126, v77, v126
	v_add_f32_e32 v126, v78, v126
	v_add_f32_e32 v126, v79, v126
	v_add_f32_e32 v120, v126, v120
	v_cvt_pk_bf16_f32 v64, v64, v65
	v_cvt_pk_bf16_f32 v65, v66, v67
	v_cvt_pk_bf16_f32 v66, v68, v69
	v_cvt_pk_bf16_f32 v67, v70, v71
	v_cvt_pk_bf16_f32 v68, v72, v73
	v_cvt_pk_bf16_f32 v69, v74, v75
	v_cvt_pk_bf16_f32 v70, v76, v77
	v_cvt_pk_bf16_f32 v71, v78, v79
	s_nop 0
	v_permlane32_swap_b32_e32 v64, v66
	v_permlane32_swap_b32_e32 v65, v67
	v_permlane32_swap_b32_e32 v68, v70
	v_permlane32_swap_b32_e32 v69, v71
	s_waitcnt lgkmcnt(0)
	s_setprio 1
	v_mfma_f32_32x32x16_bf16 v[0:15], v[64:67], v[144:147], v[0:15]
	s_sub_i32 s3, s0, s98
	s_cmp_lt_u32 s3, s100
	v_mfma_f32_32x32x16_bf16 v[48:63], v[64:67], v[152:155], v[48:63]
	v_mfma_f32_32x32x16_bf16 v[32:47], v[64:67], v[162:165], v[32:47]
	v_mfma_f32_32x32x16_bf16 v[16:31], v[64:67], v[170:173], v[16:31]
	v_mfma_f32_32x32x16_bf16 v[0:15], v[68:71], v[148:151], v[0:15]
	v_mfma_f32_32x32x16_bf16 v[48:63], v[68:71], v[156:159], v[48:63]
	v_mfma_f32_32x32x16_bf16 v[32:47], v[68:71], v[166:169], v[32:47]
	v_mfma_f32_32x32x16_bf16 v[16:31], v[68:71], v[174:177], v[16:31]
	v_mfma_f32_32x32x16_bf16 v[64:79], v[122:125], v[92:95], 0
	v_mfma_f32_32x32x16_bf16 v[64:79], v[132:135], v[88:91], v[64:79]
	v_mfma_f32_32x32x16_bf16 v[64:79], v[136:139], v[84:87], v[64:79]
	v_mfma_f32_32x32x16_bf16 v[64:79], v[140:143], v[80:83], v[64:79]
	s_setprio 0
	s_cbranch_scc1 .Ldt_d0_bias1

; #define LAS __attribute__((address_space(3)))
; DI void pv_mma(f32x16* o, const s16x4* vf, bf16x8 pa0, bf16x8 pa1) {
;     ...
; #pragma unroll
;     for (int d0 = 0; d0 < 4; ++d0) {
;         o[d0] = __builtin_amdgcn_mfma_f32_32x32x16_bf16(pa0, ATT_PK(vf[4 * d0], vf[4 * d0 + 1]), o[d0], 0, 0, 0);
;         o[d0] = __builtin_amdgcn_mfma_f32_32x32x16_bf16(pa1, ATT_PK(vf[4 * d0 + 2], vf[4 * d0 + 3]), o[d0], 0, 0, 0); }
;     ...
; }
; template <int DQK, int D0A, int D0B> DI void k_reads(bf16x8* kf, const LAS unsigned char* Ks, int half, int r32, int hi) {
; #pragma unroll
;     for (int d0 = D0A; d0 < D0B; ++d0) kf[d0 - D0A] = *(const LAS bf16x8*)(Ks + half * (32 * DQK * 2) + kswz<DQK>(r32, (d0 * 16 + hi * 8) * 2));
; }
; template <int D0A, int D0B> DI void qk_mma(f32x16& p, const bf16x8* kf, const bf16x8* qr) {
; #pragma unroll
;     for (int d0 = D0A; d0 < D0B; ++d0) {
;         if (d0 == 0) { f32x16 z; _Pragma("unroll") for (int r = 0; r < 16; ++r) z[r] = 0.f; p = __builtin_amdgcn_mfma_f32_32x32x16_bf16(kf[0], qr[0], z, 0, 0, 0); }
;         else p = __builtin_amdgcn_mfma_f32_32x32x16_bf16(kf[d0 - D0A], qr[d0], p, 0, 0, 0); }
; }
.Lstg_d0_mid_11:
	v_mfma_f32_32x32x16_bf16 v[0:15], v[64:67], v[144:147], v[0:15]
	s_sub_i32 s74, s0, s55
	s_cmp_lt_u32 s74, s100
	v_mfma_f32_32x32x16_bf16 v[48:63], v[64:67], v[152:155], v[48:63]
	v_mfma_f32_32x32x16_bf16 v[32:47], v[64:67], v[162:165], v[32:47]
	v_mfma_f32_32x32x16_bf16 v[16:31], v[64:67], v[170:173], v[16:31]
	v_mfma_f32_32x32x16_bf16 v[0:15], v[68:71], v[148:151], v[0:15]
	v_mfma_f32_32x32x16_bf16 v[48:63], v[68:71], v[156:159], v[48:63]
	v_mfma_f32_32x32x16_bf16 v[32:47], v[68:71], v[166:169], v[32:47]
	v_mfma_f32_32x32x16_bf16 v[16:31], v[68:71], v[174:177], v[16:31]
	v_mfma_f32_32x32x16_bf16 v[64:79], v[124:127], v[92:95], 0
	v_mfma_f32_32x32x16_bf16 v[64:79], v[132:135], v[88:91], v[64:79]
	v_mfma_f32_32x32x16_bf16 v[64:79], v[136:139], v[84:87], v[64:79]
	v_mfma_f32_32x32x16_bf16 v[64:79], v[140:143], v[80:83], v[64:79]
	s_cbranch_scc1 .Ldt_d0_bias2
.LBB0_1926:
	s_addk_i32 s22, 0x2000
	s_add_i32 s0, s0, 1
	v_add_u32_e32 v100, s8, v100
	v_add_u32_e32 v102, s8, v102
	s_add_u32 s7, s7, 0x100
	v_add_u32_e32 v104, s8, v104
	s_cbranch_scc1 .LBB0_1928
	s_mov_b32 s23, s64
	s_mov_b32 s64, s96
	s_mov_b32 s96, s1
	s_branch .LBB0_1920
.Ldt_d0_resc:
	s_cmp_eq_u32 s0, s98
	s_cselect_b64 s[2:3], -1, 0
	s_and_b64 vcc, s[4:5], s[2:3]
	s_cmp_eq_u32 s0, s99
	s_cselect_b64 s[2:3], -1, 0
	s_or_b64 vcc, s[2:3], vcc
	s_andn2_b64 vcc, exec, vcc
	s_cbranch_vccnz .LBB0_1922
	v_cndmask_b32_e64 v122, v112, v113, s[2:3]
	v_pk_mul_f32 v[14:15], v[14:15], v[122:123] op_sel_hi:[1,0]
	v_pk_mul_f32 v[12:13], v[12:13], v[122:123] op_sel_hi:[1,0]
	v_pk_mul_f32 v[10:11], v[10:11], v[122:123] op_sel_hi:[1,0]
	v_pk_mul_f32 v[8:9], v[8:9], v[122:123] op_sel_hi:[1,0]
	v_pk_mul_f32 v[6:7], v[6:7], v[122:123] op_sel_hi:[1,0]
	v_pk_mul_f32 v[4:5], v[4:5], v[122:123] op_sel_hi:[1,0]
	v_pk_mul_f32 v[2:3], v[2:3], v[122:123] op_sel_hi:[1,0]
	v_pk_mul_f32 v[0:1], v[0:1], v[122:123] op_sel_hi:[1,0]
	v_pk_mul_f32 v[62:63], v[62:63], v[122:123] op_sel_hi:[1,0]
	v_pk_mul_f32 v[60:61], v[60:61], v[122:123] op_sel_hi:[1,0]
	v_pk_mul_f32 v[58:59], v[58:59], v[122:123] op_sel_hi:[1,0]
	v_pk_mul_f32 v[56:57], v[56:57], v[122:123] op_sel_hi:[1,0]
	v_pk_mul_f32 v[54:55], v[54:55], v[122:123] op_sel_hi:[1,0]
	v_pk_mul_f32 v[52:53], v[52:53], v[122:123] op_sel_hi:[1,0]
	v_pk_mul_f32 v[50:51], v[50:51], v[122:123] op_sel_hi:[1,0]
	v_pk_mul_f32 v[48:49], v[48:49], v[122:123] op_sel_hi:[1,0]
	v_pk_mul_f32 v[46:47], v[46:47], v[122:123] op_sel_hi:[1,0]
	v_pk_mul_f32 v[44:45], v[44:45], v[122:123] op_sel_hi:[1,0]
	v_pk_mul_f32 v[42:43], v[42:43], v[122:123] op_sel_hi:[1,0]
	v_pk_mul_f32 v[40:41], v[40:41], v[122:123] op_sel_hi:[1,0]
	v_pk_mul_f32 v[38:39], v[38:39], v[122:123] op_sel_hi:[1,0]
	v_pk_mul_f32 v[36:37], v[36:37], v[122:123] op_sel_hi:[1,0]
	v_pk_mul_f32 v[34:35], v[34:35], v[122:123] op_sel_hi:[1,0]
	v_pk_mul_f32 v[32:33], v[32:33], v[122:123] op_sel_hi:[1,0]
	v_pk_mul_f32 v[30:31], v[30:31], v[122:123] op_sel_hi:[1,0]
	v_pk_mul_f32 v[28:29], v[28:29], v[122:123] op_sel_hi:[1,0]
	v_pk_mul_f32 v[26:27], v[26:27], v[122:123] op_sel_hi:[1,0]
	v_pk_mul_f32 v[24:25], v[24:25], v[122:123] op_sel_hi:[1,0]
	v_pk_mul_f32 v[22:23], v[22:23], v[122:123] op_sel_hi:[1,0]
	v_pk_mul_f32 v[20:21], v[20:21], v[122:123] op_sel_hi:[1,0]
	v_pk_mul_f32 v[18:19], v[18:19], v[122:123] op_sel_hi:[1,0]
	v_pk_mul_f32 v[16:17], v[16:17], v[122:123] op_sel_hi:[1,0]
	v_mul_f32_e32 v120, v120, v122
	s_branch .LBB0_1922
.Ldt_d0_bias1:
	v_add_u32_e32 v122, s7, v119
	v_add_u32_e32 v138, 0x28908, v122
	v_add_u32_e32 v140, 0x28920, v122
	v_add_u32_e32 v142, 0x28928, v122
	v_add_u32_e32 v124, 0x28940, v122
	v_add_u32_e32 v126, 0x28948, v122
	v_add_u32_e32 v132, 0x28960, v122
	v_add_u32_e32 v134, 0x28968, v122
	v_add_u32_e32 v123, 0x28900, v122
	ds_read2_b32 v[124:125], v124 offset1:1
	ds_read2_b32 v[126:127], v126 offset1:1
	ds_read2_b32 v[132:133], v132 offset1:1
	ds_read2_b32 v[134:135], v134 offset1:1
	ds_read2_b32 v[136:137], v123 offset1:1
	ds_read2_b32 v[138:139], v138 offset1:1
	ds_read2_b32 v[140:141], v140 offset1:1
	ds_read2_b32 v[142:143], v142 offset1:1
	s_waitcnt lgkmcnt(0)
	v_pk_add_f32 v[78:79], v[78:79], v[134:135]
	v_pk_add_f32 v[76:77], v[76:77], v[132:133]
	v_pk_add_f32 v[74:75], v[74:75], v[126:127]
	v_pk_add_f32 v[72:73], v[72:73], v[124:125]
	v_pk_add_f32 v[70:71], v[70:71], v[142:143]
	v_pk_add_f32 v[68:69], v[68:69], v[140:141]
	v_pk_add_f32 v[66:67], v[66:67], v[138:139]
	v_pk_add_f32 v[64:65], v[64:65], v[136:137]
	s_branch .LBB0_1924
.Ldt_d0_bias2:
	v_add_u32_e32 v122, s7, v119
	v_add_u32_e32 v136, 0x28988, v122
	v_add_u32_e32 v138, 0x289a0, v122
	v_add_u32_e32 v140, 0x289a8, v122
	v_add_u32_e32 v123, 0x289c0, v122
	v_add_u32_e32 v124, 0x289c8, v122
	v_add_u32_e32 v126, 0x289e0, v122
	v_add_u32_e32 v132, 0x289e8, v122
	v_add_u32_e32 v121, 0x28980, v122
	ds_read2_b32 v[122:123], v123 offset1:1
	ds_read2_b32 v[124:125], v124 offset1:1
	ds_read2_b32 v[126:127], v126 offset1:1
	ds_read2_b32 v[132:133], v132 offset1:1
	ds_read2_b32 v[134:135], v121 offset1:1
	ds_read2_b32 v[136:137], v136 offset1:1
	ds_read2_b32 v[138:139], v138 offset1:1
	ds_read2_b32 v[140:141], v140 offset1:1
	s_waitcnt lgkmcnt(0)
	v_pk_add_f32 v[78:79], v[78:79], v[132:133]
	v_pk_add_f32 v[76:77], v[76:77], v[126:127]
	v_pk_add_f32 v[74:75], v[74:75], v[124:125]
	v_pk_add_f32 v[72:73], v[72:73], v[122:123]
	v_pk_add_f32 v[70:71], v[70:71], v[140:141]
	v_pk_add_f32 v[68:69], v[68:69], v[138:139]
	v_pk_add_f32 v[66:67], v[66:67], v[136:137]
	v_pk_add_f32 v[64:65], v[64:65], v[134:135]
	s_branch .LBB0_1926

; DI float bf2f(unsigned short h) { return __uint_as_float((unsigned)h << 16); }
; template <int DQK, int MODE, int LDQ, int LDK, int LDV> ...
;     ...
;     float l_reg = 0.f; f32x16 o[4];
; #pragma unroll
;     for (int d = 0; d < 4; ++d)
; #pragma unroll
;         for (int r = 0; r < 16; ++r) o[d][r] = 0.f;
;     int kgo[NKP], vgo[2];
; #pragma unroll
;     for (int i = 0; i < NKP; ++i) { const int L = (wid + 8 * i) * 64 + lane, row = L / CPR, slot = L % CPR, cc = (slot & ~7) | ((slot & 7) ^ ((row >> 1) & 7)); kgo[i] = row * LDK + cc * 8; }
; #pragma unroll
;     for (int i = 0; i < 2; ++i) { const int L = (2 * wid + i) * 64 + lane, st = L >> 5, w5 = L & 31, kk = (st >> 2) * 8 + (w5 >> 2), c = (st & 3) * 32 + (w5 & 3) * 8;
;         const int k = (kk & ~0xC) | ((kk & 4) << 1) | ((kk & 8) >> 1); vgo[i] = k * LDV + c; }
;     ...
;     ATT_DMA_K(0); ATT_DMA_K(1); ATT_DMA_V(0, 0); ATT_DMA_K(2); ATT_DMA_V(1, 1);
;     bf16x8 qr[ND0];
;     { const bf16_t* Qw = Qb + (size_t)(wid * 32 + r32) * LDQ + hi * 8;
; #pragma unroll
;       for (int d0 = 0; d0 < ND0; ++d0) qr[d0] = *(const bf16x8*)(Qw + d0 * 16);
;       if constexpr (MODE == 0) {
;           float ss = 0.f;
; #pragma unroll
;           for (int d0 = 0; d0 < ND0; ++d0)
; #pragma unroll
;               for (int j = 0; j < 8; ++j) { const float f = bf2f((unsigned short)qr[d0][j]); ss += f * f; }
;           ss = swap_sum(ss);
;           const float rstd = rsqrtf(ss * (1.f / DQK) + EPS) * C;
; #pragma unroll
;           for (int d0 = 0; d0 < ND0; ++d0) { const float* g = gq + d0 * 16 + hi * 8;
;               { float f[8]; _Pragma("unroll") for (int j = 0; j < 8; ++j) f[j] = bf2f((unsigned short)qr[d0][j]) * rstd * g[j];
;                 u32x4 w = {cvtpk(f[0], f[1]), cvtpk(f[2], f[3]), cvtpk(f[4], f[5]), cvtpk(f[6], f[7])}; qr[d0] = __builtin_bit_cast(bf16x8, w); asm volatile("" ::: "memory"); } }
;       } }
;     const int qlo = q0 + wid * 32, qpos = qlo + r32;
;     const int tL = MODE == 0 ? 0 : (qlo >= 191 ? (qlo - 127) >> 6 : 0), tR = MODE == 0 ? NT : min(NT, (qlo + 222) >> 6);
;     float fL = 1.f, fR = 1.f; if constexpr (MODE != 0) { fL = __builtin_amdgcn_exp2f(bt[0]); fR = __builtin_amdgcn_exp2f(-bt[448]); }
;     ...
;     const int vbase = (int)(unsigned)(size_t)lds + V_OFF + v_rd_base(lane);
.LBB0_1950:
	s_and_b32 s44, s0, 0xffffffc0
	s_min_i32 s52, s45, 64
	s_cmp_gt_i32 s47, 0
	s_cselect_b64 s[4:5], -1, 0
	s_add_i32 s92, s92, s46
	s_add_u32 s6, s79, s90
	s_addc_u32 s7, s80, s91
	s_add_i32 s3, s3, s2
	v_lshl_add_u64 v[100:101], v[0:1], 1, s[6:7]
	v_subrev_u32_e32 v100, s34, v100
	v_add3_u32 v0, s3, v6, v4
	v_lshl_or_b32 v0, v0, 11, v3
	v_and_b32_e32 v7, 63, v7
	v_add_u32_e32 v0, v0, v5
	s_add_u32 s2, s77, s90
	v_exp_f32_e32 v112, v9
	v_lshlrev_b32_e32 v8, 3, v7
	v_lshlrev_b32_e32 v9, 4, v7
	v_lshlrev_b32_e32 v7, 1, v7
	v_ashrrev_i32_e32 v1, 31, v0
	s_addc_u32 s3, s78, s91
	v_exp_f32_e64 v113, -v10
	v_and_b32_e32 v7, 32, v7
	v_add_lshl_u32 v2, s92, v2, 2
	v_lshl_add_u64 v[102:103], v[0:1], 1, s[2:3]
	v_subrev_u32_e32 v102, s34, v102
	v_add_u32_e32 v0, 64, v0
	v_and_b32_e32 v9, 0xc0, v9
	v_and_or_b32 v7, v8, s66, v7
	v_sub_u32_e32 v2, v130, v2
	v_ashrrev_i32_e32 v1, 31, v0
	v_mov_b32_e32 v14, v131
	v_mov_b32_e32 v15, v131
	v_add3_u32 v106, v9, s93, v7
	v_add_u32_e32 v119, 0, v2
	v_lshl_add_u64 v[104:105], v[0:1], 1, s[2:3]
	v_subrev_u32_e32 v104, s34, v104
	v_mov_b32_e32 v0, v131
	v_mov_b32_e32 v1, v131
	v_mov_b32_e32 v2, v131
	v_mov_b32_e32 v3, v131
	v_mov_b32_e32 v4, v131
	v_mov_b32_e32 v5, v131
	v_mov_b32_e32 v6, v131
	v_mov_b32_e32 v7, v131
	v_mov_b32_e32 v8, v131
	v_mov_b32_e32 v9, v131
	v_mov_b32_e32 v10, v131
	v_mov_b32_e32 v11, v131
	v_mov_b32_e32 v12, v131
	v_mov_b32_e32 v13, v131
	v_mov_b64_e32 v[62:63], v[14:15]
	v_mov_b64_e32 v[30:31], v[14:15]
	v_mov_b64_e32 v[46:47], v[14:15]
	s_mov_b32 s0, 1
	s_mov_b32 s62, 0
	s_mov_b32 s1, 2
	s_sub_i32 s53, 0, s47
	s_sub_i32 s6, 0, s52
	v_mov_b32_e32 v120, 0
	s_movk_i32 s7, 0xc300
	s_movk_i32 s22, 0x6000
	s_add_i32 s98, s47, 1
	s_add_i32 s99, s52, 1
	s_sub_i32 s101, s52, s47
	s_max_i32 s100, s101, 0
	v_mov_b32_e32 v196, v107
	v_mov_b32_e32 v197, v108
	v_mov_b32_e32 v198, v109
	v_mov_b32_e32 v199, v110
	v_mov_b64_e32 v[60:61], v[12:13]
	v_mov_b64_e32 v[58:59], v[10:11]
	v_mov_b64_e32 v[56:57], v[8:9]
	v_mov_b64_e32 v[54:55], v[6:7]
	v_mov_b64_e32 v[52:53], v[4:5]
	v_mov_b64_e32 v[50:51], v[2:3]
	v_mov_b64_e32 v[48:49], v[0:1]
	v_mov_b64_e32 v[28:29], v[12:13]
	v_mov_b64_e32 v[26:27], v[10:11]
	v_mov_b64_e32 v[24:25], v[8:9]
	v_mov_b64_e32 v[22:23], v[6:7]
	v_mov_b64_e32 v[20:21], v[4:5]
	v_mov_b64_e32 v[18:19], v[2:3]
	v_mov_b64_e32 v[16:17], v[0:1]
	v_mov_b64_e32 v[44:45], v[12:13]
	v_mov_b64_e32 v[42:43], v[10:11]
	v_mov_b64_e32 v[40:41], v[8:9]
	v_mov_b64_e32 v[38:39], v[6:7]
	v_mov_b64_e32 v[36:37], v[4:5]
	v_mov_b64_e32 v[34:35], v[2:3]
	v_mov_b64_e32 v[32:33], v[0:1]
	s_mov_b32 s49, 1
	s_cmp_lt_u32 s33, 0x100
	s_cbranch_scc1 .Lstg_d1_pre_17
	s_waitcnt vmcnt(3)
	s_barrier

; #define LAS __attribute__((address_space(3)))
; DI void expsum(f32x16& p, float& l_reg, bf16x8& pa0, bf16x8& pa1) {
; #pragma unroll
;     for (int r = 0; r < 16; ++r) p[r] = __builtin_amdgcn_exp2f(p[r]);
;     float ps = 0.f;
; #pragma unroll
;     for (int r = 0; r < 16; ++r) ps += p[r];
;     l_reg += ps; asm volatile("" : "+v"(l_reg));
;     ...
;     ATT_PK4(p, 0, pa0); ATT_PK4(p, 8, pa1);
;     ...
; }
; DI int v_rd_base(int lane) { return ((lane & 3) << 3) | (((lane >> 2) & 3) << 6) | (((lane >> 4) & 1) << 5) | (((lane >> 5) & 1) << 8); }
; template <int OFF> DI s16x4 tr_read(int vb) { s16x4 r; asm volatile("ds_read_b64_tr_b16 %0, %1 offset:%2" : "=&v"(r) : "v"(vb), "i"(OFF) : "memory"); return r; }
; template <int H> DI void v_reads(s16x4* vf, int vb) {
;     vf[0] = tr_read<v_rd_off(0, 2 * H, 0)>(vb); vf[1] = tr_read<v_rd_off(0, 2 * H, 1)>(vb); vf[2] = tr_read<v_rd_off(0, 2 * H + 1, 0)>(vb); vf[3] = tr_read<v_rd_off(0, 2 * H + 1, 1)>(vb);
;     vf[4] = tr_read<v_rd_off(1, 2 * H, 0)>(vb); vf[5] = tr_read<v_rd_off(1, 2 * H, 1)>(vb); vf[6] = tr_read<v_rd_off(1, 2 * H + 1, 0)>(vb); vf[7] = tr_read<v_rd_off(1, 2 * H + 1, 1)>(vb);
;     vf[8] = tr_read<v_rd_off(2, 2 * H, 0)>(vb); vf[9] = tr_read<v_rd_off(2, 2 * H, 1)>(vb); vf[10] = tr_read<v_rd_off(2, 2 * H + 1, 0)>(vb); vf[11] = tr_read<v_rd_off(2, 2 * H + 1, 1)>(vb);
;     vf[12] = tr_read<v_rd_off(3, 2 * H, 0)>(vb); vf[13] = tr_read<v_rd_off(3, 2 * H, 1)>(vb); vf[14] = tr_read<v_rd_off(3, 2 * H + 1, 0)>(vb); vf[15] = tr_read<v_rd_off(3, 2 * H + 1, 1)>(vb);
; }
; DI void pv_mma(f32x16* o, const s16x4* vf, bf16x8 pa0, bf16x8 pa1) {
;     ...
; #pragma unroll
;     for (int d0 = 0; d0 < 4; ++d0) {
;         o[d0] = __builtin_amdgcn_mfma_f32_32x32x16_bf16(pa0, ATT_PK(vf[4 * d0], vf[4 * d0 + 1]), o[d0], 0, 0, 0);
;         o[d0] = __builtin_amdgcn_mfma_f32_32x32x16_bf16(pa1, ATT_PK(vf[4 * d0 + 2], vf[4 * d0 + 3]), o[d0], 0, 0, 0); }
;     ...
; }
; template <int DQK, int D0A, int D0B> DI void k_reads(bf16x8* kf, const LAS unsigned char* Ks, int half, int r32, int hi) {
; #pragma unroll
;     for (int d0 = D0A; d0 < D0B; ++d0) kf[d0 - D0A] = *(const LAS bf16x8*)(Ks + half * (32 * DQK * 2) + kswz<DQK>(r32, (d0 * 16 + hi * 8) * 2));
; }
; template <int D0A, int D0B> DI void qk_mma(f32x16& p, const bf16x8* kf, const bf16x8* qr) {
; #pragma unroll
;     for (int d0 = D0A; d0 < D0B; ++d0) {
.Lstg_d1_top_18:
	s_setprio 0
	s_add_i32 s2, s48, s2
	global_load_lds_dwordx4 v100, s[34:35]
	s_add_i32 s3, s2, 0x400
	s_mov_b32 m0, s2
	s_sub_i32 s74, s0, s98
	global_load_lds_dwordx4 v102, s[34:35]
	s_mov_b32 m0, s3
	s_cmp_le_u32 s74, s101
	global_load_lds_dwordx4 v104, s[34:35]
	s_mov_b32 s23, s62
	s_cbranch_scc1 .Ldt_d1_resc
.LBB0_1953:
	ds_read_b128 v[122:125], v196 offset:4096
	ds_read_b128 v[132:135], v197 offset:4096
	s_lshl_b32 s2, s23, 14
	ds_read_b128 v[136:139], v198 offset:4096
	ds_read_b128 v[140:143], v199 offset:4096
	v_add_u32_e32 v121, s2, v106
	ds_read_b64_tr_b16 v[144:145], v121 offset:0
	ds_read_b64_tr_b16 v[146:147], v121 offset:0x800
	ds_read_b64_tr_b16 v[148:149], v121 offset:0x1000
	ds_read_b64_tr_b16 v[150:151], v121 offset:0x1800
	ds_read_b64_tr_b16 v[152:153], v121 offset:0x200
	ds_read_b64_tr_b16 v[154:155], v121 offset:0xa00
	ds_read_b64_tr_b16 v[156:157], v121 offset:0x1200
	ds_read_b64_tr_b16 v[158:159], v121 offset:0x1a00
	ds_read_b64_tr_b16 v[162:163], v121 offset:0x400
	ds_read_b64_tr_b16 v[164:165], v121 offset:0xc00
	ds_read_b64_tr_b16 v[166:167], v121 offset:0x1400
	ds_read_b64_tr_b16 v[168:169], v121 offset:0x1c00
	ds_read_b64_tr_b16 v[170:171], v121 offset:0x600
	ds_read_b64_tr_b16 v[172:173], v121 offset:0xe00
	ds_read_b64_tr_b16 v[174:175], v121 offset:0x1600
	ds_read_b64_tr_b16 v[176:177], v121 offset:0x1e00
	s_setprio 2
	v_exp_f32_e32 v64, v64
	v_exp_f32_e32 v65, v65
	v_exp_f32_e32 v66, v66
	v_exp_f32_e32 v67, v67
	v_exp_f32_e32 v68, v68
	v_exp_f32_e32 v69, v69
	v_add_f32_e32 v126, v65, v64
	v_exp_f32_e32 v70, v70
	v_add_f32_e32 v126, v66, v126
	v_exp_f32_e32 v71, v71
	v_add_f32_e32 v126, v67, v126
	v_exp_f32_e32 v72, v72
	v_add_f32_e32 v126, v68, v126
	v_exp_f32_e32 v73, v73
	v_add_f32_e32 v126, v69, v126
	v_exp_f32_e32 v74, v74
	v_add_f32_e32 v126, v70, v126
	v_exp_f32_e32 v75, v75
	v_add_f32_e32 v126, v71, v126
	v_exp_f32_e32 v76, v76
	v_add_f32_e32 v126, v72, v126
	v_exp_f32_e32 v77, v77
	v_add_f32_e32 v126, v73, v126
	v_exp_f32_e32 v78, v78
	v_add_f32_e32 v126, v74, v126
	v_exp_f32_e32 v79, v79
	v_add_f32_e32 v126, v75, v126
	v_add_f32_e32 v126, v76, v126
	v_add_f32_e32 v126, v77, v126
	v_add_f32_e32 v126, v78, v126
	v_add_f32_e32 v126, v79, v126
	v_add_f32_e32 v120, v126, v120
	v_cvt_pk_bf16_f32 v64, v64, v65
	v_cvt_pk_bf16_f32 v65, v66, v67
	v_cvt_pk_bf16_f32 v66, v68, v69
	v_cvt_pk_bf16_f32 v67, v70, v71
	v_cvt_pk_bf16_f32 v68, v72, v73
	v_cvt_pk_bf16_f32 v69, v74, v75
	v_cvt_pk_bf16_f32 v70, v76, v77
	v_cvt_pk_bf16_f32 v71, v78, v79
	s_nop 0
	v_permlane32_swap_b32_e32 v64, v66
	v_permlane32_swap_b32_e32 v65, v67
	v_permlane32_swap_b32_e32 v68, v70
	v_permlane32_swap_b32_e32 v69, v71
	s_waitcnt lgkmcnt(0)
	s_setprio 1
	v_mfma_f32_32x32x16_bf16 v[0:15], v[64:67], v[144:147], v[0:15]
	s_sub_i32 s3, s0, s98
	s_cmp_lt_u32 s3, s100
	v_mfma_f32_32x32x16_bf16 v[48:63], v[64:67], v[152:155], v[48:63]
	v_mfma_f32_32x32x16_bf16 v[16:31], v[64:67], v[162:165], v[16:31]
	v_mfma_f32_32x32x16_bf16 v[32:47], v[64:67], v[170:173], v[32:47]
	v_mfma_f32_32x32x16_bf16 v[0:15], v[68:71], v[148:151], v[0:15]
	v_mfma_f32_32x32x16_bf16 v[48:63], v[68:71], v[156:159], v[48:63]
	v_mfma_f32_32x32x16_bf16 v[16:31], v[68:71], v[166:169], v[16:31]
	v_mfma_f32_32x32x16_bf16 v[32:47], v[68:71], v[174:177], v[32:47]
	v_mfma_f32_32x32x16_bf16 v[64:79], v[122:125], v[92:95], 0
	v_mfma_f32_32x32x16_bf16 v[64:79], v[132:135], v[88:91], v[64:79]
	v_mfma_f32_32x32x16_bf16 v[64:79], v[136:139], v[84:87], v[64:79]
	v_mfma_f32_32x32x16_bf16 v[64:79], v[140:143], v[80:83], v[64:79]
	s_setprio 0
	s_cbranch_scc1 .Ldt_d1_bias1

; #define LAS __attribute__((address_space(3)))
; DI void pv_mma(f32x16* o, const s16x4* vf, bf16x8 pa0, bf16x8 pa1) {
;     ...
; #pragma unroll
;     for (int d0 = 0; d0 < 4; ++d0) {
;         o[d0] = __builtin_amdgcn_mfma_f32_32x32x16_bf16(pa0, ATT_PK(vf[4 * d0], vf[4 * d0 + 1]), o[d0], 0, 0, 0);
;         o[d0] = __builtin_amdgcn_mfma_f32_32x32x16_bf16(pa1, ATT_PK(vf[4 * d0 + 2], vf[4 * d0 + 3]), o[d0], 0, 0, 0); }
;     ...
; }
; template <int DQK, int D0A, int D0B> DI void k_reads(bf16x8* kf, const LAS unsigned char* Ks, int half, int r32, int hi) {
; #pragma unroll
;     for (int d0 = D0A; d0 < D0B; ++d0) kf[d0 - D0A] = *(const LAS bf16x8*)(Ks + half * (32 * DQK * 2) + kswz<DQK>(r32, (d0 * 16 + hi * 8) * 2));
; }
; template <int D0A, int D0B> DI void qk_mma(f32x16& p, const bf16x8* kf, const bf16x8* qr) {
; #pragma unroll
;     for (int d0 = D0A; d0 < D0B; ++d0) {
;         if (d0 == 0) { f32x16 z; _Pragma("unroll") for (int r = 0; r < 16; ++r) z[r] = 0.f; p = __builtin_amdgcn_mfma_f32_32x32x16_bf16(kf[0], qr[0], z, 0, 0, 0); }
;         else p = __builtin_amdgcn_mfma_f32_32x32x16_bf16(kf[d0 - D0A], qr[d0], p, 0, 0, 0); }
; }
.Lstg_d1_mid_19:
	v_mfma_f32_32x32x16_bf16 v[0:15], v[64:67], v[144:147], v[0:15]
	s_sub_i32 s74, s0, s47
	s_cmp_lt_u32 s74, s100
	v_mfma_f32_32x32x16_bf16 v[48:63], v[64:67], v[152:155], v[48:63]
	v_mfma_f32_32x32x16_bf16 v[16:31], v[64:67], v[162:165], v[16:31]
	v_mfma_f32_32x32x16_bf16 v[32:47], v[64:67], v[170:173], v[32:47]
	v_mfma_f32_32x32x16_bf16 v[0:15], v[68:71], v[148:151], v[0:15]
	v_mfma_f32_32x32x16_bf16 v[48:63], v[68:71], v[156:159], v[48:63]
	v_mfma_f32_32x32x16_bf16 v[16:31], v[68:71], v[166:169], v[16:31]
	v_mfma_f32_32x32x16_bf16 v[32:47], v[68:71], v[174:177], v[32:47]
	v_mfma_f32_32x32x16_bf16 v[64:79], v[124:127], v[92:95], 0
	v_mfma_f32_32x32x16_bf16 v[64:79], v[132:135], v[88:91], v[64:79]
	v_mfma_f32_32x32x16_bf16 v[64:79], v[136:139], v[84:87], v[64:79]
	v_mfma_f32_32x32x16_bf16 v[64:79], v[140:143], v[80:83], v[64:79]
	s_cbranch_scc1 .Ldt_d1_bias2
.LBB0_1957:
	s_addk_i32 s22, 0x2000
	s_add_i32 s0, s0, 1
	v_add_u32_e32 v100, s8, v100
	v_add_u32_e32 v102, s8, v102
	s_add_u32 s7, s7, 0x100
	v_add_u32_e32 v104, s8, v104
	s_cbranch_scc1 .LBB0_1959
	s_mov_b32 s62, s49
	s_mov_b32 s49, s1
	s_mov_b32 s1, s23
	s_branch .LBB0_1951
.Ldt_d1_resc:
	s_cmp_eq_u32 s0, s98
	s_cselect_b64 s[2:3], -1, 0
	s_and_b64 vcc, s[4:5], s[2:3]
	s_cmp_eq_u32 s0, s99
	s_cselect_b64 s[2:3], -1, 0
	s_or_b64 vcc, s[2:3], vcc
	s_andn2_b64 vcc, exec, vcc
	s_cbranch_vccnz .LBB0_1953
	v_cndmask_b32_e64 v122, v112, v113, s[2:3]
	v_pk_mul_f32 v[14:15], v[14:15], v[122:123] op_sel_hi:[1,0]
	v_pk_mul_f32 v[12:13], v[12:13], v[122:123] op_sel_hi:[1,0]
	v_pk_mul_f32 v[10:11], v[10:11], v[122:123] op_sel_hi:[1,0]
	v_pk_mul_f32 v[8:9], v[8:9], v[122:123] op_sel_hi:[1,0]
	v_pk_mul_f32 v[6:7], v[6:7], v[122:123] op_sel_hi:[1,0]
	v_pk_mul_f32 v[4:5], v[4:5], v[122:123] op_sel_hi:[1,0]
	v_pk_mul_f32 v[2:3], v[2:3], v[122:123] op_sel_hi:[1,0]
	v_pk_mul_f32 v[0:1], v[0:1], v[122:123] op_sel_hi:[1,0]
	v_pk_mul_f32 v[62:63], v[62:63], v[122:123] op_sel_hi:[1,0]
	v_pk_mul_f32 v[60:61], v[60:61], v[122:123] op_sel_hi:[1,0]
	v_pk_mul_f32 v[58:59], v[58:59], v[122:123] op_sel_hi:[1,0]
	v_pk_mul_f32 v[56:57], v[56:57], v[122:123] op_sel_hi:[1,0]
	v_pk_mul_f32 v[54:55], v[54:55], v[122:123] op_sel_hi:[1,0]
	v_pk_mul_f32 v[52:53], v[52:53], v[122:123] op_sel_hi:[1,0]
	v_pk_mul_f32 v[50:51], v[50:51], v[122:123] op_sel_hi:[1,0]
	v_pk_mul_f32 v[48:49], v[48:49], v[122:123] op_sel_hi:[1,0]
	v_pk_mul_f32 v[30:31], v[30:31], v[122:123] op_sel_hi:[1,0]
	v_pk_mul_f32 v[28:29], v[28:29], v[122:123] op_sel_hi:[1,0]
	v_pk_mul_f32 v[26:27], v[26:27], v[122:123] op_sel_hi:[1,0]
	v_pk_mul_f32 v[24:25], v[24:25], v[122:123] op_sel_hi:[1,0]
	v_pk_mul_f32 v[22:23], v[22:23], v[122:123] op_sel_hi:[1,0]
	v_pk_mul_f32 v[20:21], v[20:21], v[122:123] op_sel_hi:[1,0]
	v_pk_mul_f32 v[18:19], v[18:19], v[122:123] op_sel_hi:[1,0]
	v_pk_mul_f32 v[16:17], v[16:17], v[122:123] op_sel_hi:[1,0]
	v_pk_mul_f32 v[46:47], v[46:47], v[122:123] op_sel_hi:[1,0]
	v_pk_mul_f32 v[44:45], v[44:45], v[122:123] op_sel_hi:[1,0]
	v_pk_mul_f32 v[42:43], v[42:43], v[122:123] op_sel_hi:[1,0]
	v_pk_mul_f32 v[40:41], v[40:41], v[122:123] op_sel_hi:[1,0]
	v_pk_mul_f32 v[38:39], v[38:39], v[122:123] op_sel_hi:[1,0]
	v_pk_mul_f32 v[36:37], v[36:37], v[122:123] op_sel_hi:[1,0]
	v_pk_mul_f32 v[34:35], v[34:35], v[122:123] op_sel_hi:[1,0]
	v_pk_mul_f32 v[32:33], v[32:33], v[122:123] op_sel_hi:[1,0]
	v_mul_f32_e32 v120, v120, v122
	s_branch .LBB0_1953
